# phase 3: blocks < 128 run their long cross-chunk GLA scan first (while memory is quiet) and their S5 item second
# speedup vs baseline: 1.0102x; 1.0046x over previous
; DEVINL void run_phase(const Params& p, char* smem, int ph) {
;     ...
;       for (int it = bid; it < S5CP_BLK + GLAB_ITEMS + S5CS_BLK; it += nb) {
;         if (it < S5CP_BLK) { __syncthreads(); s5_passC_prompt(p, smem, it); }
;         else if (it < S5CP_BLK + GLAB_ITEMS) gla_passB(p, it - S5CP_BLK);
;         else { __syncthreads(); s5_passC_sample(p, smem, it - S5CP_BLK - GLAB_ITEMS); }
;       }
.LBB0_448:
	s_and_b64 vcc, exec, s[0:1]
	s_cbranch_vccz .LBB0_534
	s_cmpk_gt_i32 s14, 0xe7f
	s_cbranch_scc1 .LBB0_533
	s_lshl_b32 s0, s14, 5
	s_addk_i32 s0, 0xc000
	s_waitcnt vmcnt(0)
	v_lshlrev_b32_e32 v1, 5, v104
	s_mov_b64 s[40:41], 0
	s_waitcnt lgkmcnt(0)
	v_mov_b32_e32 v75, s14
	v_mov_b32_e32 v78, s0
	v_mov_b32_e32 v79, s14
	v_cmp_gt_u32_e32 vcc, 0x80, v79
	v_mov_b32_e32 v197, 0x200
	v_cmp_eq_u32_e64 s[0:1], v197, v104
	s_and_b64 vcc, vcc, s[0:1]
	v_mov_b32_e32 v196, 0
	v_mov_b32_e32 v197, 0x200
	s_nop 0
	v_cndmask_b32_e32 v196, v196, v197, vcc
	v_add_u32_e32 v79, v79, v196
	v_add_u16_e32 v75, v75, v196
	v_lshlrev_b32_e32 v197, 5, v196
	v_add_u32_e32 v78, v78, v197
	s_branch .LBB0_453

; DEVINL void run_phase(const Params& p, char* smem, int ph) {
;     ...
;       for (int it = bid; it < S5CP_BLK + GLAB_ITEMS + S5CS_BLK; it += nb) {
;         if (it < S5CP_BLK) { __syncthreads(); s5_passC_prompt(p, smem, it); }
;         else if (it < S5CP_BLK + GLAB_ITEMS) gla_passB(p, it - S5CP_BLK);
;         else { __syncthreads(); s5_passC_sample(p, smem, it - S5CP_BLK - GLAB_ITEMS); }
;       }
.LBB0_452:
	s_or_b64 exec, exec, s[42:43]
	v_mov_b32_e32 v196, 0x180
	v_cmp_gt_i32_e32 vcc, 0x200, v79
	s_nop 1
	v_cndmask_b32_e32 v196, v196, v104, vcc
	v_mov_b32_e32 v197, 0x2000
	v_cmp_gt_i32_e32 vcc, 0x80, v79
	s_nop 1
	v_cndmask_b32_e32 v196, v196, v197, vcc
	v_subrev_u32_e32 v197, 0x200, v79
	v_cmp_gt_u32_e32 vcc, 0x80, v197
	v_mov_b32_e32 v197, 0xfffffe00
	s_nop 0
	v_cndmask_b32_e32 v196, v196, v197, vcc
	v_cmp_ne_u32_e32 vcc, 0x200, v104
	s_nop 1
	v_cndmask_b32_e32 v196, v196, v104, vcc
	v_add_u32_e32 v79, v79, v196
	s_movk_i32 s0, 0xe7f
	v_cmp_lt_i32_e32 vcc, s0, v79
	v_lshlrev_b32_e32 v197, 5, v196
	v_add_u32_e32 v78, v78, v197
	s_or_b64 s[40:41], vcc, s[40:41]
	v_add_u16_e32 v75, v75, v196
	s_andn2_b64 exec, exec, s[40:41]
	s_cbranch_execz .LBB0_532
